# nt policy on P7 (y stores, x2 loads) and P0 once-read f32 loads (w_in, x); on top of v35
# speedup vs baseline: 1.0318x; 1.0318x over previous
.LBB0_14:
	s_mul_hi_i32 s39, s38, 0x2aaaaaab
	s_lshr_b32 s40, s39, 31
	s_ashr_i32 s39, s39, 5
	v_mov_b32_e32 v1, v0
	s_add_i32 s40, s39, s40
	s_mul_i32 s39, s40, 0xffffd000
	v_bfe_u32 v6, v1, 4, 2
	v_lshl_or_b32 v7, s40, 6, v6
	s_add_i32 s42, s15, s39
	v_lshlrev_b32_e32 v4, 4, v1
	v_mul_u32_u24_e32 v10, 0x104, v6
	v_mad_i64_i32 v[6:7], s[44:45], v7, s17, v[2:3]
	s_ashr_i32 s43, s42, 31
	v_and_b32_e32 v4, 0xf0, v4
	v_lshl_add_u64 v[6:7], s[42:43], 2, v[6:7]
	v_lshl_add_u64 v[6:7], v[6:7], 0, v[4:5]
	v_add_co_u32_e32 v20, vcc, s18, v6
	global_load_dwordx4 v[22:25], v[6:7], off nt
	s_nop 0
	v_addc_co_u32_e32 v21, vcc, 0, v7, vcc
	v_add_co_u32_e32 v30, vcc, s19, v6
	s_ashr_i32 s44, s42, 8
	s_nop 0
	v_addc_co_u32_e32 v31, vcc, 0, v7, vcc
	v_add_co_u32_e32 v34, vcc, s20, v6
	s_ashr_i32 s41, s40, 31
	s_nop 0
	v_addc_co_u32_e32 v35, vcc, 0, v7, vcc
	v_add_co_u32_e32 v38, vcc, s21, v6
	s_ashr_i32 s45, s44, 31
	s_nop 0
	v_addc_co_u32_e32 v39, vcc, 0, v7, vcc
	v_add_co_u32_e32 v42, vcc, s22, v6
	s_lshl_b64 s[40:41], s[40:41], 15
	s_nop 0
	v_addc_co_u32_e32 v43, vcc, 0, v7, vcc
	v_add_co_u32_e32 v46, vcc, s23, v6
	s_lshl_b64 s[44:45], s[44:45], 21
	s_nop 0
	v_addc_co_u32_e32 v47, vcc, 0, v7, vcc
	v_add_co_u32_e32 v50, vcc, s24, v6
	v_bfe_u32 v8, v1, 3, 3
	s_nop 0
	v_addc_co_u32_e32 v51, vcc, 0, v7, vcc
	v_add_co_u32_e32 v54, vcc, s25, v6
	v_lshlrev_b32_e32 v1, 3, v1
	s_nop 0
	v_addc_co_u32_e32 v55, vcc, 0, v7, vcc
	v_add_co_u32_e32 v58, vcc, s26, v6
	v_add3_u32 v86, s2, v10, v4
	s_nop 0
	v_addc_co_u32_e32 v59, vcc, 0, v7, vcc
	v_add_co_u32_e32 v62, vcc, s27, v6
	s_add_u32 s39, s3, s44
	s_nop 0
	v_addc_co_u32_e32 v63, vcc, 0, v7, vcc
	v_add_co_u32_e32 v66, vcc, s28, v6
	v_and_b32_e32 v1, 56, v1
	s_nop 0
	v_addc_co_u32_e32 v67, vcc, 0, v7, vcc
	v_add_co_u32_e32 v70, vcc, s29, v6
	v_add_u32_e32 v87, 0x410, v86
	s_nop 0
	v_addc_co_u32_e32 v71, vcc, 0, v7, vcc
	v_add_co_u32_e32 v74, vcc, s30, v6
	v_add_u32_e32 v88, 0x418, v86
	s_nop 0
	v_addc_co_u32_e32 v75, vcc, 0, v7, vcc
	v_add_co_u32_e32 v78, vcc, s31, v6
	v_add_u32_e32 v89, 0x820, v86
	s_nop 0
	v_addc_co_u32_e32 v79, vcc, 0, v7, vcc
	v_add_co_u32_e32 v6, vcc, s33, v6
	v_add_u32_e32 v90, 0x828, v86
	s_nop 0
	v_addc_co_u32_e32 v7, vcc, 0, v7, vcc
	global_load_dwordx4 v[26:29], v[20:21], off nt
	s_nop 0
	global_load_dwordx4 v[30:33], v[30:31], off nt
	s_nop 0
	global_load_dwordx4 v[34:37], v[34:35], off nt
	s_nop 0
	global_load_dwordx4 v[38:41], v[38:39], off nt
	s_nop 0
	global_load_dwordx4 v[42:45], v[42:43], off nt
	s_nop 0
	global_load_dwordx4 v[46:49], v[46:47], off nt
	s_nop 0
	global_load_dwordx4 v[50:53], v[50:51], off nt
	s_nop 0
	global_load_dwordx4 v[54:57], v[54:55], off nt
	s_nop 0
	global_load_dwordx4 v[58:61], v[58:59], off nt
	s_nop 0
	global_load_dwordx4 v[62:65], v[62:63], off nt
	s_nop 0
	global_load_dwordx4 v[66:69], v[66:67], off nt
	s_nop 0
	global_load_dwordx4 v[70:73], v[70:71], off nt
	s_nop 0
	global_load_dwordx4 v[74:77], v[74:75], off nt
	s_nop 0
	global_load_dwordx4 v[78:81], v[78:79], off nt
	s_nop 0
	global_load_dwordx4 v[82:85], v[6:7], off nt
	v_add_u32_e32 v91, 0xc30, v86
	v_add_u32_e32 v92, 0xc38, v86
	v_add_u32_e32 v93, 0x1040, v86
	v_add_u32_e32 v94, 0x1048, v86
	v_add_u32_e32 v95, 0x1450, v86
	v_add_u32_e32 v96, 0x1458, v86
	v_add_u32_e32 v97, 0x1860, v86
	v_add_u32_e32 v98, 0x1868, v86
	v_add_u32_e32 v99, 0x1c70, v86
	v_add_u32_e32 v100, 0x1c78, v86
	v_add_u32_e32 v101, 0x2080, v86
	v_add_u32_e32 v102, 0x2088, v86
	v_add_u32_e32 v103, 0x2490, v86
	v_add_u32_e32 v104, 0x2498, v86
	v_add_u32_e32 v105, 0x28a0, v86
	v_add_u32_e32 v106, 0x28a8, v86
	v_add_u32_e32 v107, 0x2cb0, v86
	v_add_u32_e32 v108, 0x2cb8, v86
	v_add_u32_e32 v109, 0x30c0, v86
	v_add_u32_e32 v110, 0x30c8, v86
	v_add_u32_e32 v111, 0x34d0, v86
	v_add_u32_e32 v112, 0x34d8, v86
	v_add_u32_e32 v113, 0x38e0, v86
	v_add_u32_e32 v114, 0x38e8, v86
	v_add_u32_e32 v115, 0x3cf0, v86
	v_add_u32_e32 v116, 0x3cf8, v86
	s_addc_u32 s43, s14, s45
	s_waitcnt vmcnt(15)
	ds_write2_b32 v86, v22, v23 offset1:1
	ds_write2_b32 v86, v24, v25 offset0:2 offset1:3
	s_waitcnt vmcnt(14)
	ds_write2_b32 v87, v26, v27 offset1:1
	ds_write2_b32 v88, v28, v29 offset1:1
	s_waitcnt vmcnt(13)
	ds_write2_b32 v89, v30, v31 offset1:1
	ds_write2_b32 v90, v32, v33 offset1:1
	s_waitcnt vmcnt(12)
	ds_write2_b32 v91, v34, v35 offset1:1
	ds_write2_b32 v92, v36, v37 offset1:1
	s_waitcnt vmcnt(11)
	ds_write2_b32 v93, v38, v39 offset1:1
	ds_write2_b32 v94, v40, v41 offset1:1
	s_waitcnt vmcnt(10)
	ds_write2_b32 v95, v42, v43 offset1:1
	ds_write2_b32 v96, v44, v45 offset1:1
	s_waitcnt vmcnt(9)
	ds_write2_b32 v97, v46, v47 offset1:1
	ds_write2_b32 v98, v48, v49 offset1:1
	s_waitcnt vmcnt(8)
	ds_write2_b32 v99, v50, v51 offset1:1
	ds_write2_b32 v100, v52, v53 offset1:1
	s_waitcnt vmcnt(7)
	ds_write2_b32 v101, v54, v55 offset1:1
	ds_write2_b32 v102, v56, v57 offset1:1
	s_waitcnt vmcnt(6)
	ds_write2_b32 v103, v58, v59 offset1:1
	ds_write2_b32 v104, v60, v61 offset1:1
	s_waitcnt vmcnt(5)
	ds_write2_b32 v105, v62, v63 offset1:1
	ds_write2_b32 v106, v64, v65 offset1:1
	s_waitcnt vmcnt(4)
	ds_write2_b32 v107, v66, v67 offset1:1
	ds_write2_b32 v108, v68, v69 offset1:1
	s_waitcnt vmcnt(3)
	ds_write2_b32 v109, v70, v71 offset1:1
	ds_write2_b32 v110, v72, v73 offset1:1
	s_waitcnt vmcnt(2)
	ds_write2_b32 v111, v74, v75 offset1:1
	ds_write2_b32 v112, v76, v77 offset1:1
	s_waitcnt vmcnt(1)
	ds_write2_b32 v113, v78, v79 offset1:1
	ds_write2_b32 v114, v80, v81 offset1:1
	s_waitcnt vmcnt(0)
	ds_write2_b32 v115, v82, v83 offset1:1
	ds_write2_b32 v116, v84, v85 offset1:1
	v_lshlrev_b32_e32 v12, 2, v8
	v_mul_u32_u24_e32 v10, 0x104, v1
	s_add_u32 s40, s39, s40
	s_waitcnt lgkmcnt(0)
	v_add3_u32 v117, s2, v10, v12
	s_addc_u32 s41, s43, s41
	s_and_b32 s39, s42, 0xc0
	v_add_u32_e32 v118, 0x400, v117
	v_lshlrev_b32_e32 v4, 1, v1
	v_or_b32_e32 v1, s39, v8
	ds_read2_b32 v[22:23], v117 offset0:65 offset1:73
	ds_read2_b32 v[24:25], v117 offset1:8
	ds_read2_b32 v[26:27], v117 offset0:130 offset1:138
	ds_read2_b32 v[28:29], v117 offset0:195 offset1:203
	ds_read2_b32 v[30:31], v118 offset0:4 offset1:12
	ds_read2_b32 v[32:33], v118 offset0:69 offset1:77
	ds_read2_b32 v[34:35], v118 offset0:134 offset1:142
	ds_read2_b32 v[36:37], v118 offset0:199 offset1:207
	ds_read2_b32 v[38:39], v117 offset0:81 offset1:89
	ds_read2_b32 v[40:41], v117 offset0:16 offset1:24
	ds_read2_b32 v[42:43], v117 offset0:146 offset1:154
	ds_read2_b32 v[44:45], v117 offset0:211 offset1:219
	ds_read2_b32 v[46:47], v118 offset0:20 offset1:28
	ds_read2_b32 v[48:49], v118 offset0:85 offset1:93
	ds_read2_b32 v[50:51], v118 offset0:150 offset1:158
	ds_read2_b32 v[52:53], v118 offset0:215 offset1:223
	ds_read2_b32 v[54:55], v117 offset0:32 offset1:40
	ds_read2_b32 v[56:57], v117 offset0:97 offset1:105
	ds_read2_b32 v[58:59], v117 offset0:162 offset1:170
	ds_read2_b32 v[60:61], v117 offset0:227 offset1:235
	ds_read2_b32 v[62:63], v118 offset0:36 offset1:44
	ds_read2_b32 v[64:65], v118 offset0:101 offset1:109
	ds_read2_b32 v[66:67], v118 offset0:166 offset1:174
	ds_read2_b32 v[68:69], v118 offset0:231 offset1:239
	ds_read2_b32 v[70:71], v117 offset0:48 offset1:56
	ds_read2_b32 v[72:73], v117 offset0:113 offset1:121
	ds_read2_b32 v[74:75], v117 offset0:178 offset1:186
	ds_read2_b32 v[76:77], v117 offset0:243 offset1:251
	ds_read2_b32 v[78:79], v118 offset0:52 offset1:60
	ds_read2_b32 v[80:81], v118 offset0:117 offset1:125
	ds_read2_b32 v[82:83], v118 offset0:182 offset1:190
	ds_read2_b32 v[84:85], v118 offset0:247 offset1:255
	v_lshl_add_u64 v[20:21], s[40:41], 0, v[4:5]
	v_lshlrev_b32_e32 v4, 7, v1
	v_mov_b32_e32 v9, v5
	v_mov_b32_e32 v11, v5
	v_mov_b32_e32 v13, v5
	v_mov_b32_e32 v15, v5
	v_mov_b32_e32 v17, v5
	v_mov_b32_e32 v19, v5
	v_lshl_add_u64 v[6:7], v[20:21], 0, v[4:5]
	v_or_b32_e32 v8, 0x400, v4
	v_or_b32_e32 v10, 0x800, v4
	v_or_b32_e32 v12, 0xc00, v4
	v_or_b32_e32 v14, 0x1000, v4
	v_or_b32_e32 v16, 0x1400, v4
	v_or_b32_e32 v18, 0x1800, v4
	v_or_b32_e32 v4, 0x1c00, v4
	v_lshl_add_u64 v[8:9], v[20:21], 0, v[8:9]
	v_lshl_add_u64 v[10:11], v[20:21], 0, v[10:11]
	v_lshl_add_u64 v[12:13], v[20:21], 0, v[12:13]
	v_lshl_add_u64 v[14:15], v[20:21], 0, v[14:15]
	v_lshl_add_u64 v[16:17], v[20:21], 0, v[16:17]
	v_lshl_add_u64 v[18:19], v[20:21], 0, v[18:19]
	v_lshl_add_u64 v[20:21], v[20:21], 0, v[4:5]
	s_waitcnt lgkmcnt(14)
	v_bfe_u32 v1, v24, 16, 1
	v_bfe_u32 v4, v22, 16, 1
	v_bfe_u32 v86, v25, 16, 1
	v_bfe_u32 v87, v26, 16, 1
	v_bfe_u32 v89, v28, 16, 1
	v_bfe_u32 v91, v30, 16, 1
	v_bfe_u32 v94, v31, 16, 1
	v_bfe_u32 v95, v34, 16, 1
	v_bfe_u32 v88, v23, 16, 1
	v_bfe_u32 v90, v27, 16, 1
	v_bfe_u32 v92, v29, 16, 1
	v_bfe_u32 v93, v32, 16, 1
	v_bfe_u32 v96, v33, 16, 1
	v_bfe_u32 v97, v36, 16, 1
	v_bfe_u32 v98, v35, 16, 1
	v_bfe_u32 v99, v37, 16, 1
	v_bfe_u32 v100, v40, 16, 1
	v_bfe_u32 v101, v38, 16, 1
	v_bfe_u32 v102, v41, 16, 1
	v_bfe_u32 v103, v42, 16, 1
	v_bfe_u32 v104, v39, 16, 1
	v_bfe_u32 v105, v44, 16, 1
	v_bfe_u32 v106, v43, 16, 1
	v_bfe_u32 v107, v46, 16, 1
	v_bfe_u32 v108, v45, 16, 1
	v_bfe_u32 v109, v48, 16, 1
	v_bfe_u32 v110, v47, 16, 1
	v_bfe_u32 v111, v50, 16, 1
	v_bfe_u32 v112, v49, 16, 1
	v_bfe_u32 v113, v52, 16, 1
	v_bfe_u32 v114, v51, 16, 1
	v_bfe_u32 v115, v53, 16, 1
	v_bfe_u32 v116, v54, 16, 1
	v_bfe_u32 v117, v56, 16, 1
	v_bfe_u32 v118, v55, 16, 1
	s_waitcnt lgkmcnt(13)
	v_bfe_u32 v119, v58, 16, 1
	v_bfe_u32 v120, v57, 16, 1
	s_waitcnt lgkmcnt(12)
	v_bfe_u32 v121, v60, 16, 1
	v_bfe_u32 v122, v59, 16, 1
	s_waitcnt lgkmcnt(11)
	v_bfe_u32 v123, v62, 16, 1
	v_bfe_u32 v124, v61, 16, 1
	s_waitcnt lgkmcnt(10)
	v_bfe_u32 v125, v64, 16, 1
	v_bfe_u32 v126, v63, 16, 1
	s_waitcnt lgkmcnt(9)
	v_bfe_u32 v127, v66, 16, 1
	v_bfe_u32 v128, v65, 16, 1
	s_waitcnt lgkmcnt(8)
	v_bfe_u32 v129, v68, 16, 1
	v_bfe_u32 v130, v67, 16, 1
	v_bfe_u32 v131, v69, 16, 1
	s_waitcnt lgkmcnt(7)
	v_bfe_u32 v132, v70, 16, 1
	v_bfe_u32 v133, v71, 16, 1
	s_waitcnt lgkmcnt(6)
	v_bfe_u32 v134, v72, 16, 1
	v_bfe_u32 v135, v73, 16, 1
	s_waitcnt lgkmcnt(5)
	v_bfe_u32 v136, v74, 16, 1
	v_bfe_u32 v137, v75, 16, 1
	s_waitcnt lgkmcnt(4)
	v_bfe_u32 v138, v76, 16, 1
	v_bfe_u32 v139, v77, 16, 1
	s_waitcnt lgkmcnt(3)
	v_bfe_u32 v140, v78, 16, 1
	v_bfe_u32 v141, v79, 16, 1
	s_waitcnt lgkmcnt(2)
	v_bfe_u32 v142, v80, 16, 1
	s_waitcnt lgkmcnt(1)
	v_bfe_u32 v144, v82, 16, 1
	v_bfe_u32 v145, v83, 16, 1
	v_add3_u32 v1, v24, v1, s36
	v_add3_u32 v24, v25, v86, s36
	v_add3_u32 v4, v22, v4, s36
	v_add3_u32 v22, v26, v87, s36
	v_add3_u32 v25, v28, v89, s36
	v_add3_u32 v26, v30, v91, s36
	v_add3_u32 v28, v31, v94, s36
	v_add3_u32 v31, v34, v95, s36
	v_bfe_u32 v143, v81, 16, 1
	s_waitcnt lgkmcnt(0)
	v_bfe_u32 v146, v84, 16, 1
	v_bfe_u32 v147, v85, 16, 1
	v_add3_u32 v86, v23, v88, s36
	v_add3_u32 v23, v27, v90, s36
	v_add3_u32 v27, v29, v92, s36
	v_add3_u32 v29, v32, v93, s36
	v_add3_u32 v30, v33, v96, s36
	v_add3_u32 v32, v35, v98, s36
	v_add3_u32 v33, v36, v97, s36
	v_add3_u32 v34, v37, v99, s36
	v_add3_u32 v35, v40, v100, s36
	v_add3_u32 v36, v41, v102, s36
	v_add3_u32 v37, v38, v101, s36
	v_add3_u32 v38, v39, v104, s36
	v_add3_u32 v39, v42, v103, s36
	v_add3_u32 v40, v43, v106, s36
	v_add3_u32 v41, v44, v105, s36
	v_add3_u32 v42, v45, v108, s36
	v_add3_u32 v43, v46, v107, s36
	v_add3_u32 v44, v47, v110, s36
	v_add3_u32 v45, v48, v109, s36
	v_add3_u32 v46, v49, v112, s36
	v_add3_u32 v47, v50, v111, s36
	v_add3_u32 v48, v51, v114, s36
	v_add3_u32 v49, v52, v113, s36
	v_add3_u32 v50, v53, v115, s36
	v_add3_u32 v51, v54, v116, s36
	v_add3_u32 v52, v55, v118, s36
	v_add3_u32 v53, v56, v117, s36
	v_add3_u32 v54, v57, v120, s36
	v_add3_u32 v55, v58, v119, s36
	v_add3_u32 v56, v59, v122, s36
	v_add3_u32 v57, v60, v121, s36
	v_add3_u32 v58, v61, v124, s36
	v_add3_u32 v59, v62, v123, s36
	v_add3_u32 v60, v63, v126, s36
	v_add3_u32 v61, v64, v125, s36
	v_add3_u32 v62, v65, v128, s36
	v_add3_u32 v63, v66, v127, s36
	v_add3_u32 v64, v67, v130, s36
	v_add3_u32 v65, v68, v129, s36
	v_add3_u32 v66, v69, v131, s36
	v_add3_u32 v67, v70, v132, s36
	v_add3_u32 v68, v71, v133, s36
	v_add3_u32 v69, v72, v134, s36
	v_add3_u32 v70, v73, v135, s36
	v_add3_u32 v71, v74, v136, s36
	v_add3_u32 v72, v75, v137, s36
	v_add3_u32 v73, v76, v138, s36
	v_add3_u32 v74, v77, v139, s36
	v_add3_u32 v75, v78, v140, s36
	v_add3_u32 v76, v79, v141, s36
	v_add3_u32 v77, v80, v142, s36
	v_add3_u32 v79, v82, v144, s36
	v_add3_u32 v80, v83, v145, s36
	v_lshrrev_b32_e32 v1, 16, v1
	v_lshrrev_b32_e32 v83, 16, v22
	v_lshrrev_b32_e32 v26, 16, v26
	v_lshrrev_b32_e32 v31, 16, v31
	v_add3_u32 v78, v81, v143, s36
	v_add3_u32 v81, v84, v146, s36
	v_add3_u32 v82, v85, v147, s36
	v_lshrrev_b32_e32 v84, 16, v24
	v_lshrrev_b32_e32 v85, 16, v23
	v_lshrrev_b32_e32 v28, 16, v28
	v_lshrrev_b32_e32 v32, 16, v32
	v_lshrrev_b32_e32 v35, 16, v35
	v_lshrrev_b32_e32 v39, 16, v39
	v_lshrrev_b32_e32 v43, 16, v43
	v_lshrrev_b32_e32 v47, 16, v47
	v_lshrrev_b32_e32 v36, 16, v36
	v_lshrrev_b32_e32 v40, 16, v40
	v_lshrrev_b32_e32 v44, 16, v44
	v_lshrrev_b32_e32 v48, 16, v48
	v_lshrrev_b32_e32 v51, 16, v51
	v_lshrrev_b32_e32 v55, 16, v55
	v_lshrrev_b32_e32 v59, 16, v59
	v_lshrrev_b32_e32 v63, 16, v63
	v_lshrrev_b32_e32 v52, 16, v52
	v_lshrrev_b32_e32 v56, 16, v56
	v_lshrrev_b32_e32 v60, 16, v60
	v_lshrrev_b32_e32 v64, 16, v64
	v_lshrrev_b32_e32 v67, 16, v67
	v_lshrrev_b32_e32 v71, 16, v71
	v_lshrrev_b32_e32 v75, 16, v75
	v_lshrrev_b32_e32 v79, 16, v79
	v_lshrrev_b32_e32 v68, 16, v68
	v_lshrrev_b32_e32 v72, 16, v72
	v_lshrrev_b32_e32 v76, 16, v76
	v_lshrrev_b32_e32 v80, 16, v80
	v_and_or_b32 v22, v4, s37, v1
	v_and_or_b32 v23, v25, s37, v83
	v_and_or_b32 v24, v29, s37, v26
	v_and_or_b32 v25, v33, s37, v31
	v_and_or_b32 v26, v86, s37, v84
	v_and_or_b32 v27, v27, s37, v85
	v_and_or_b32 v28, v30, s37, v28
	v_and_or_b32 v29, v34, s37, v32
	v_and_or_b32 v30, v37, s37, v35
	v_and_or_b32 v31, v41, s37, v39
	v_and_or_b32 v32, v45, s37, v43
	v_and_or_b32 v33, v49, s37, v47
	v_and_or_b32 v34, v38, s37, v36
	v_and_or_b32 v35, v42, s37, v40
	v_and_or_b32 v36, v46, s37, v44
	v_and_or_b32 v37, v50, s37, v48
	v_and_or_b32 v38, v53, s37, v51
	v_and_or_b32 v39, v57, s37, v55
	v_and_or_b32 v40, v61, s37, v59
	v_and_or_b32 v41, v65, s37, v63
	v_and_or_b32 v42, v54, s37, v52
	v_and_or_b32 v43, v58, s37, v56
	v_and_or_b32 v44, v62, s37, v60
	v_and_or_b32 v45, v66, s37, v64
	v_and_or_b32 v46, v69, s37, v67
	v_and_or_b32 v47, v73, s37, v71
	v_and_or_b32 v48, v77, s37, v75
	v_and_or_b32 v49, v81, s37, v79
	v_and_or_b32 v50, v70, s37, v68
	v_and_or_b32 v51, v74, s37, v72
	v_and_or_b32 v52, v78, s37, v76
	v_and_or_b32 v53, v82, s37, v80
	global_store_dwordx4 v[6:7], v[22:25], off
	global_store_dwordx4 v[8:9], v[26:29], off
	global_store_dwordx4 v[10:11], v[30:33], off
	global_store_dwordx4 v[12:13], v[34:37], off
	global_store_dwordx4 v[14:15], v[38:41], off
	global_store_dwordx4 v[16:17], v[42:45], off
	global_store_dwordx4 v[18:19], v[46:49], off
	global_store_dwordx4 v[20:21], v[50:53], off
	s_waitcnt lgkmcnt(0)
	s_add_i32 s38, s38, s84
	s_add_i32 s15, s15, s16
	s_cmpk_gt_i32 s38, 0x2fff
	s_cbranch_scc0 .LBB0_14

.LBB0_17:
	v_mov_b32_e32 v2, v0
	s_nop 0
	v_and_b32_e32 v78, 63, v2
	v_lshlrev_b32_e32 v66, 4, v78
	v_lshl_add_u64 v[2:3], s[4:5], 0, v[66:67]
	v_add_co_u32_e32 v4, vcc, s22, v2
	global_load_dwordx4 v[62:65], v66, s[4:5] nt
	global_load_dwordx4 v[58:61], v66, s[4:5] offset:1024 nt
	global_load_dwordx4 v[54:57], v66, s[4:5] offset:2048 nt
	global_load_dwordx4 v[46:49], v66, s[4:5] offset:3072 nt
	v_addc_co_u32_e32 v5, vcc, 0, v3, vcc
	global_load_dwordx4 v[34:37], v[4:5], off offset:-4096 nt
	v_add_co_u32_e32 v6, vcc, s23, v2
	s_waitcnt vmcnt(4)
	v_mul_f32_e32 v77, v63, v63
	v_addc_co_u32_e32 v7, vcc, 0, v3, vcc
	global_load_dwordx4 v[30:33], v[6:7], off offset:1024 nt
	global_load_dwordx4 v[22:25], v[6:7], off offset:2048 nt
	global_load_dwordx4 v[10:13], v[6:7], off offset:3072 nt
	global_load_dwordx4 v[50:53], v[4:5], off nt
	global_load_dwordx4 v[42:45], v[4:5], off offset:1024 nt
	global_load_dwordx4 v[38:41], v[4:5], off offset:2048 nt
	global_load_dwordx4 v[26:29], v[4:5], off offset:3072 nt
	v_add_co_u32_e32 v84, vcc, s24, v2
	v_mul_f32_e32 v79, v65, v65
	s_nop 0
	v_addc_co_u32_e32 v85, vcc, 0, v3, vcc
	global_load_dwordx4 v[18:21], v[84:85], off nt
	global_load_dwordx4 v[80:83], v66, s[10:11]
	global_load_dwordx4 v[14:17], v[84:85], off offset:1024 nt
	global_load_dwordx4 v[6:9], v[84:85], off offset:2048 nt
	global_load_dwordx4 v[2:5], v[84:85], off offset:3072 nt
	s_waitcnt vmcnt(15)
	v_mul_f32_e32 v84, v59, v59
	v_mul_f32_e32 v85, v61, v61
	s_waitcnt vmcnt(14)
	v_mul_f32_e32 v86, v55, v55
	v_mul_f32_e32 v87, v57, v57
	v_fmac_f32_e32 v77, v62, v62
	v_fmac_f32_e32 v79, v64, v64
	v_fmac_f32_e32 v84, v58, v58
	v_fmac_f32_e32 v85, v60, v60
	s_waitcnt vmcnt(13)
	v_mul_f32_e32 v88, v47, v47
	v_mul_f32_e32 v89, v49, v49
	v_fmac_f32_e32 v86, v54, v54
	v_fmac_f32_e32 v87, v56, v56
	v_add_f32_e32 v77, v77, v79
	v_add_f32_e32 v79, v84, v85
	v_fmac_f32_e32 v88, v46, v46
	v_fmac_f32_e32 v89, v48, v48
	v_add_f32_e32 v84, v86, v87
	s_waitcnt vmcnt(12)
	v_mul_f32_e32 v86, v35, v35
	v_mul_f32_e32 v87, v37, v37
	v_add_f32_e32 v77, v77, v79
	v_add_f32_e32 v85, v88, v89
	v_fmac_f32_e32 v86, v34, v34
	v_fmac_f32_e32 v87, v36, v36
	v_add_f32_e32 v77, v77, v84
	v_add_f32_e32 v79, v86, v87
	v_add_f32_e32 v77, v77, v85
	v_add_f32_e32 v77, v77, v79
	v_cmp_lt_i32_e32 vcc, v69, v68
	s_waitcnt vmcnt(11)
	v_mul_f32_e32 v88, v31, v31
	v_mul_f32_e32 v89, v33, v33
	s_waitcnt vmcnt(10)
	v_mul_f32_e32 v90, v23, v23
	v_mul_f32_e32 v91, v25, v25
	v_fmac_f32_e32 v88, v30, v30
	v_fmac_f32_e32 v89, v32, v32
	s_waitcnt vmcnt(9)
	v_mul_f32_e32 v92, v11, v11
	v_mul_f32_e32 v93, v13, v13
	v_fmac_f32_e32 v90, v22, v22
	v_fmac_f32_e32 v91, v24, v24
	v_add_f32_e32 v84, v88, v89
	s_waitcnt vmcnt(8)
	v_mul_f32_e32 v94, v51, v51
	v_mul_f32_e32 v95, v53, v53
	v_fmac_f32_e32 v92, v10, v10
	v_fmac_f32_e32 v93, v12, v12
	v_add_f32_e32 v86, v90, v91
	v_add_f32_e32 v77, v77, v84
	s_waitcnt vmcnt(7)
	v_mul_f32_e32 v96, v43, v43
	v_mul_f32_e32 v97, v45, v45
	v_fmac_f32_e32 v94, v50, v50
	v_fmac_f32_e32 v95, v52, v52
	v_add_f32_e32 v87, v92, v93
	v_add_f32_e32 v77, v77, v86
	s_waitcnt vmcnt(6)
	v_mul_f32_e32 v98, v39, v39
	v_mul_f32_e32 v99, v41, v41
	v_fmac_f32_e32 v96, v42, v42
	v_fmac_f32_e32 v97, v44, v44
	v_add_f32_e32 v88, v94, v95
	v_add_f32_e32 v77, v77, v87
	v_fmac_f32_e32 v98, v38, v38
	v_add_f32_e32 v89, v96, v97
	v_fmac_f32_e32 v99, v40, v40
	v_add_f32_e32 v77, v77, v88
	s_waitcnt vmcnt(5)
	v_mul_f32_e32 v79, v27, v27
	v_mul_f32_e32 v84, v29, v29
	v_add_f32_e32 v90, v98, v99
	v_add_f32_e32 v77, v77, v89
	v_fmac_f32_e32 v79, v26, v26
	v_fmac_f32_e32 v84, v28, v28
	v_add_f32_e32 v77, v77, v90
	v_add_f32_e32 v79, v79, v84
	v_add_f32_e32 v77, v77, v79
	s_waitcnt vmcnt(4)
	v_mul_f32_e32 v79, v19, v19
	v_mul_f32_e32 v84, v21, v21
	v_fmac_f32_e32 v79, v18, v18
	v_fmac_f32_e32 v84, v20, v20
	v_add_f32_e32 v79, v79, v84
	v_add_f32_e32 v77, v77, v79
	s_waitcnt vmcnt(2)
	v_mul_f32_e32 v79, v15, v15
	v_mul_f32_e32 v84, v17, v17
	v_fmac_f32_e32 v79, v14, v14
	v_fmac_f32_e32 v84, v16, v16
	v_add_f32_e32 v79, v79, v84
	v_add_f32_e32 v77, v77, v79
	s_waitcnt vmcnt(1)
	v_mul_f32_e32 v79, v7, v7
	v_mul_f32_e32 v84, v9, v9
	v_fmac_f32_e32 v79, v6, v6
	v_fmac_f32_e32 v84, v8, v8
	v_add_f32_e32 v79, v79, v84
	v_add_f32_e32 v77, v77, v79
	s_waitcnt vmcnt(0)
	v_mul_f32_e32 v79, v3, v3
	v_mul_f32_e32 v84, v5, v5
	v_fmac_f32_e32 v79, v2, v2
	v_fmac_f32_e32 v84, v4, v4
	v_add_f32_e32 v79, v79, v84
	v_add_f32_e32 v77, v77, v79
	v_cndmask_b32_e32 v79, v1, v69, vcc
	v_lshlrev_b32_e32 v79, 2, v79
	ds_bpermute_b32 v79, v79, v77
	v_cmp_lt_i32_e32 vcc, v70, v68
	s_waitcnt lgkmcnt(0)
	v_add_f32_e32 v77, v77, v79
	v_cndmask_b32_e32 v79, v1, v70, vcc
	v_lshlrev_b32_e32 v79, 2, v79
	ds_bpermute_b32 v79, v79, v77
	v_cmp_lt_i32_e32 vcc, v71, v68
	s_waitcnt lgkmcnt(0)
	v_add_f32_e32 v77, v77, v79
	v_cndmask_b32_e32 v79, v1, v71, vcc
	v_lshlrev_b32_e32 v79, 2, v79
	ds_bpermute_b32 v79, v79, v77
	v_cmp_lt_i32_e32 vcc, v72, v68
	s_waitcnt lgkmcnt(0)
	v_add_f32_e32 v77, v77, v79
	v_cndmask_b32_e32 v79, v1, v72, vcc
	v_lshlrev_b32_e32 v79, 2, v79
	ds_bpermute_b32 v79, v79, v77
	v_cmp_lt_i32_e32 vcc, v73, v68
	s_waitcnt lgkmcnt(0)
	v_add_f32_e32 v77, v77, v79
	v_cndmask_b32_e32 v79, v1, v73, vcc
	v_lshlrev_b32_e32 v79, 2, v79
	ds_bpermute_b32 v79, v79, v77
	v_cmp_lt_i32_e32 vcc, v74, v68
	s_waitcnt lgkmcnt(0)
	v_add_f32_e32 v77, v77, v79
	v_cndmask_b32_e32 v79, v1, v74, vcc
	v_lshlrev_b32_e32 v79, 2, v79
	ds_bpermute_b32 v79, v79, v77
	s_waitcnt lgkmcnt(0)
	v_add_f32_e32 v77, v77, v79
	v_fmamk_f32 v77, v77, 0x39800000, v75
	v_mul_f32_e32 v79, 0x4f800000, v77
	v_cmp_gt_f32_e32 vcc, s25, v77
	s_nop 1
	v_cndmask_b32_e32 v77, v77, v79, vcc
	v_sqrt_f32_e32 v79, v77
	s_nop 0
	v_add_u32_e32 v84, -1, v79
	v_fma_f32 v85, -v84, v79, v77
	v_cmp_ge_f32_e64 s[4:5], 0, v85
	v_add_u32_e32 v85, 1, v79
	s_nop 0
	v_cndmask_b32_e64 v84, v79, v84, s[4:5]
	v_fma_f32 v79, -v85, v79, v77
	v_cmp_lt_f32_e64 s[4:5], 0, v79
	s_nop 1
	v_cndmask_b32_e64 v79, v84, v85, s[4:5]
	v_mul_f32_e32 v84, 0x37800000, v79
	v_cndmask_b32_e32 v79, v79, v84, vcc
	v_cmp_class_f32_e32 vcc, v77, v76
	s_nop 1
	v_cndmask_b32_e32 v77, v79, v77, vcc
	v_div_scale_f32 v79, s[4:5], v77, v77, 1.0
	v_rcp_f32_e32 v84, v79
	s_lshl_b64 s[4:5], s[20:21], 13
	s_add_u32 s4, s2, s4
	s_addc_u32 s5, s3, s5
	v_fma_f32 v85, -v79, v84, 1.0
	v_fmac_f32_e32 v84, v85, v84
	v_div_scale_f32 v85, vcc, 1.0, v77, 1.0
	v_mul_f32_e32 v86, v85, v84
	v_fma_f32 v87, -v79, v86, v85
	v_fmac_f32_e32 v86, v87, v84
	v_fma_f32 v79, -v79, v86, v85
	v_div_fmas_f32 v79, v79, v84, v86
	v_div_fixup_f32 v77, v79, v77, 1.0
	v_mul_f32_e32 v62, v62, v77
	v_mul_f32_e32 v63, v63, v77
	v_mul_f32_e32 v62, v80, v62
	v_mul_f32_e32 v64, v64, v77
	v_mul_f32_e32 v63, v81, v63
	v_bfe_u32 v79, v62, 16, 1
	v_mul_f32_e32 v65, v65, v77
	v_mul_f32_e32 v64, v82, v64
	v_add3_u32 v62, v62, v79, s26
	v_bfe_u32 v79, v63, 16, 1
	v_mul_f32_e32 v65, v83, v65
	v_add3_u32 v63, v63, v79, s26
	v_bfe_u32 v79, v64, 16, 1
	v_add3_u32 v79, v64, v79, s26
	v_bfe_u32 v64, v65, 16, 1
	v_lshrrev_b32_e32 v62, 16, v62
	v_add3_u32 v65, v65, v64, s26
	v_and_or_b32 v64, v63, s27, v62
	v_lshrrev_b32_e32 v62, 16, v79
	v_and_or_b32 v65, v65, s27, v62
	v_lshlrev_b32_e32 v62, 3, v78
	global_store_dwordx2 v62, v[64:65], s[4:5]
	v_mov_b32_e32 v78, v104
	v_mov_b32_e32 v79, v105
	v_mov_b32_e32 v80, v106
	v_mov_b32_e32 v81, v107
	v_mul_f32_e32 v58, v58, v77
	v_mul_f32_e32 v60, v60, v77
	v_mul_f32_e32 v59, v59, v77
	v_mul_f32_e32 v61, v61, v77
	v_mul_f32_e32 v54, v54, v77
	v_mul_f32_e32 v56, v56, v77
	v_mul_f32_e32 v55, v55, v77
	v_mul_f32_e32 v57, v57, v77
	v_mul_f32_e32 v46, v46, v77
	v_mul_f32_e32 v48, v48, v77
	v_mul_f32_e32 v47, v47, v77
	v_mul_f32_e32 v49, v49, v77
	v_mul_f32_e32 v34, v34, v77
	v_mul_f32_e32 v36, v36, v77
	v_mul_f32_e32 v35, v35, v77
	v_mul_f32_e32 v37, v37, v77
	v_mul_f32_e32 v30, v30, v77
	v_mul_f32_e32 v32, v32, v77
	v_mul_f32_e32 v31, v31, v77
	v_mul_f32_e32 v33, v33, v77
	v_mul_f32_e32 v22, v22, v77
	v_mul_f32_e32 v24, v24, v77
	v_mul_f32_e32 v23, v23, v77
	v_mul_f32_e32 v25, v25, v77
	v_mul_f32_e32 v10, v10, v77
	v_mul_f32_e32 v12, v12, v77
	v_mul_f32_e32 v11, v11, v77
	v_mul_f32_e32 v13, v13, v77
	v_mul_f32_e32 v6, v6, v77
	v_mul_f32_e32 v8, v8, v77
	v_mul_f32_e32 v7, v7, v77
	v_mul_f32_e32 v9, v9, v77
	v_mul_f32_e32 v2, v2, v77
	v_mul_f32_e32 v4, v4, v77
	s_add_u32 s18, s18, s84
	v_mul_f32_e32 v3, v3, v77
	v_mul_f32_e32 v5, v5, v77
	s_addc_u32 s19, s19, s85
	s_add_u32 s12, s12, s14
	s_addc_u32 s13, s13, s15
	s_cmpk_gt_i32 s18, 0x20ff
	v_mul_f32_e32 v58, v78, v58
	v_mul_f32_e32 v60, v80, v60
	v_mul_f32_e32 v59, v79, v59
	v_mul_f32_e32 v61, v81, v61
	v_bfe_u32 v63, v58, 16, 1
	v_bfe_u32 v65, v60, 16, 1
	v_bfe_u32 v64, v59, 16, 1
	v_bfe_u32 v78, v61, 16, 1
	v_add3_u32 v58, v58, v63, s26
	v_add3_u32 v60, v60, v65, s26
	v_add3_u32 v59, v59, v64, s26
	v_add3_u32 v61, v61, v78, s26
	v_lshrrev_b32_e32 v58, 16, v58
	v_lshrrev_b32_e32 v60, 16, v60
	v_and_or_b32 v58, v59, s27, v58
	v_and_or_b32 v59, v61, s27, v60
	global_store_dwordx2 v62, v[58:59], s[4:5] offset:512
	v_mov_b32_e32 v58, v108
	v_mov_b32_e32 v59, v109
	v_mov_b32_e32 v60, v110
	v_mov_b32_e32 v61, v111
	v_mov_b32_e32 v63, v67
	v_mul_f32_e32 v54, v58, v54
	v_mul_f32_e32 v56, v60, v56
	v_mul_f32_e32 v55, v59, v55
	v_mul_f32_e32 v57, v61, v57
	v_bfe_u32 v58, v54, 16, 1
	v_bfe_u32 v60, v56, 16, 1
	v_bfe_u32 v59, v55, 16, 1
	v_bfe_u32 v61, v57, 16, 1
	v_add3_u32 v54, v54, v58, s26
	v_add3_u32 v56, v56, v60, s26
	v_add3_u32 v55, v55, v59, s26
	v_add3_u32 v57, v57, v61, s26
	v_lshrrev_b32_e32 v54, 16, v54
	v_lshrrev_b32_e32 v56, 16, v56
	v_and_or_b32 v54, v55, s27, v54
	v_and_or_b32 v55, v57, s27, v56
	global_store_dwordx2 v62, v[54:55], s[4:5] offset:1024
	v_mov_b32_e32 v58, v112
	v_mov_b32_e32 v59, v113
	v_mov_b32_e32 v60, v114
	v_mov_b32_e32 v61, v115
	v_lshl_add_u64 v[54:55], s[10:11], 0, v[66:67]
	v_add_co_u32_e32 v56, vcc, s22, v54
	v_mul_f32_e32 v46, v58, v46
	v_mul_f32_e32 v48, v60, v48
	v_mul_f32_e32 v47, v59, v47
	v_mul_f32_e32 v49, v61, v49
	v_bfe_u32 v58, v46, 16, 1
	v_bfe_u32 v60, v48, 16, 1
	v_bfe_u32 v59, v47, 16, 1
	v_bfe_u32 v61, v49, 16, 1
	v_add3_u32 v46, v46, v58, s26
	v_add3_u32 v48, v48, v60, s26
	v_add3_u32 v47, v47, v59, s26
	v_add3_u32 v49, v49, v61, s26
	v_lshrrev_b32_e32 v46, 16, v46
	v_lshrrev_b32_e32 v48, 16, v48
	v_and_or_b32 v46, v47, s27, v46
	v_and_or_b32 v47, v49, s27, v48
	v_addc_co_u32_e32 v57, vcc, 0, v55, vcc
	global_store_dwordx2 v62, v[46:47], s[4:5] offset:1536
	v_mov_b32_e32 v46, v116
	v_mov_b32_e32 v47, v117
	v_mov_b32_e32 v48, v118
	v_mov_b32_e32 v49, v119
	v_add_co_u32_e32 v58, vcc, s23, v54
	v_mul_f32_e32 v34, v34, v46
	v_mul_f32_e32 v36, v36, v48
	v_mul_f32_e32 v35, v35, v47
	v_mul_f32_e32 v37, v37, v49
	v_bfe_u32 v46, v34, 16, 1
	v_bfe_u32 v48, v36, 16, 1
	v_bfe_u32 v47, v35, 16, 1
	v_bfe_u32 v49, v37, 16, 1
	v_add3_u32 v34, v34, v46, s26
	v_add3_u32 v36, v36, v48, s26
	v_add3_u32 v35, v35, v47, s26
	v_add3_u32 v37, v37, v49, s26
	v_lshrrev_b32_e32 v34, 16, v34
	v_lshrrev_b32_e32 v36, 16, v36
	v_and_or_b32 v34, v35, s27, v34
	v_and_or_b32 v35, v37, s27, v36
	v_addc_co_u32_e32 v59, vcc, 0, v55, vcc
	global_store_dwordx2 v62, v[34:35], s[4:5] offset:2048
	v_mov_b32_e32 v34, v120
	v_mov_b32_e32 v35, v121
	v_mov_b32_e32 v36, v122
	v_mov_b32_e32 v37, v123
	v_mul_f32_e32 v30, v30, v34
	v_mul_f32_e32 v32, v32, v36
	v_mul_f32_e32 v31, v31, v35
	v_mul_f32_e32 v33, v33, v37
	v_bfe_u32 v34, v30, 16, 1
	v_bfe_u32 v36, v32, 16, 1
	v_bfe_u32 v35, v31, 16, 1
	v_bfe_u32 v37, v33, 16, 1
	v_add3_u32 v30, v30, v34, s26
	v_add3_u32 v32, v32, v36, s26
	v_add3_u32 v31, v31, v35, s26
	v_add3_u32 v33, v33, v37, s26
	v_lshrrev_b32_e32 v30, 16, v30
	v_lshrrev_b32_e32 v32, 16, v32
	v_and_or_b32 v30, v31, s27, v30
	v_and_or_b32 v31, v33, s27, v32
	global_store_dwordx2 v62, v[30:31], s[4:5] offset:2560
	v_mov_b32_e32 v30, v124
	v_mov_b32_e32 v31, v125
	v_mov_b32_e32 v32, v126
	v_mov_b32_e32 v33, v127
	v_mul_f32_e32 v22, v22, v30
	v_mul_f32_e32 v24, v24, v32
	v_mul_f32_e32 v23, v23, v31
	v_mul_f32_e32 v25, v25, v33
	v_bfe_u32 v30, v22, 16, 1
	v_bfe_u32 v32, v24, 16, 1
	v_bfe_u32 v31, v23, 16, 1
	v_bfe_u32 v33, v25, 16, 1
	v_add3_u32 v22, v22, v30, s26
	v_add3_u32 v24, v24, v32, s26
	v_add3_u32 v23, v23, v31, s26
	v_add3_u32 v25, v25, v33, s26
	v_lshrrev_b32_e32 v22, 16, v22
	v_lshrrev_b32_e32 v24, 16, v24
	v_and_or_b32 v22, v23, s27, v22
	v_and_or_b32 v23, v25, s27, v24
	global_store_dwordx2 v62, v[22:23], s[4:5] offset:3072
	v_mov_b32_e32 v22, v128
	v_mov_b32_e32 v23, v129
	v_mov_b32_e32 v24, v130
	v_mov_b32_e32 v25, v131
	v_mul_f32_e32 v30, v52, v77
	v_mul_f32_e32 v31, v53, v77
	v_mul_f32_e32 v10, v10, v22
	v_mul_f32_e32 v12, v12, v24
	v_mul_f32_e32 v11, v11, v23
	v_mul_f32_e32 v13, v13, v25
	v_bfe_u32 v22, v10, 16, 1
	v_bfe_u32 v24, v12, 16, 1
	v_bfe_u32 v23, v11, 16, 1
	v_bfe_u32 v25, v13, 16, 1
	v_add3_u32 v10, v10, v22, s26
	v_add3_u32 v12, v12, v24, s26
	v_add3_u32 v11, v11, v23, s26
	v_add3_u32 v13, v13, v25, s26
	v_lshrrev_b32_e32 v10, 16, v10
	v_lshrrev_b32_e32 v12, 16, v12
	v_and_or_b32 v10, v11, s27, v10
	v_and_or_b32 v11, v13, s27, v12
	global_store_dwordx2 v62, v[10:11], s[4:5] offset:3584
	v_mov_b32_e32 v22, v132
	v_mov_b32_e32 v23, v133
	v_mov_b32_e32 v24, v134
	v_mov_b32_e32 v25, v135
	v_mul_f32_e32 v12, v50, v77
	v_mul_f32_e32 v13, v51, v77
	v_lshl_add_u64 v[10:11], s[4:5], 0, v[62:63]
	v_add_co_u32_e32 v10, vcc, s23, v10
	v_mul_f32_e32 v12, v12, v22
	v_mul_f32_e32 v22, v30, v24
	v_mul_f32_e32 v13, v13, v23
	v_mul_f32_e32 v23, v31, v25
	v_bfe_u32 v24, v12, 16, 1
	v_bfe_u32 v30, v22, 16, 1
	v_bfe_u32 v25, v13, 16, 1
	v_bfe_u32 v31, v23, 16, 1
	v_add3_u32 v12, v12, v24, s26
	v_add3_u32 v22, v22, v30, s26
	v_add3_u32 v13, v13, v25, s26
	v_add3_u32 v23, v23, v31, s26
	v_lshrrev_b32_e32 v12, 16, v12
	v_lshrrev_b32_e32 v22, 16, v22
	v_addc_co_u32_e32 v11, vcc, 0, v11, vcc
	v_and_or_b32 v12, v13, s27, v12
	v_and_or_b32 v13, v23, s27, v22
	global_store_dwordx2 v[10:11], v[12:13], off
	v_mov_b32_e32 v22, v136
	v_mov_b32_e32 v23, v137
	v_mov_b32_e32 v24, v138
	v_mov_b32_e32 v25, v139
	v_mul_f32_e32 v12, v42, v77
	v_mul_f32_e32 v30, v44, v77
	v_mul_f32_e32 v13, v43, v77
	v_mul_f32_e32 v31, v45, v77
	v_mul_f32_e32 v12, v12, v22
	v_mul_f32_e32 v22, v30, v24
	v_mul_f32_e32 v13, v13, v23
	v_mul_f32_e32 v23, v31, v25
	v_bfe_u32 v24, v12, 16, 1
	v_bfe_u32 v30, v22, 16, 1
	v_bfe_u32 v25, v13, 16, 1
	v_bfe_u32 v31, v23, 16, 1
	v_add3_u32 v12, v12, v24, s26
	v_add3_u32 v22, v22, v30, s26
	v_add3_u32 v13, v13, v25, s26
	v_add3_u32 v23, v23, v31, s26
	v_lshrrev_b32_e32 v12, 16, v12
	v_lshrrev_b32_e32 v22, 16, v22
	v_and_or_b32 v12, v13, s27, v12
	v_and_or_b32 v13, v23, s27, v22
	global_store_dwordx2 v[10:11], v[12:13], off offset:512
	v_mov_b32_e32 v22, v140
	v_mov_b32_e32 v23, v141
	v_mov_b32_e32 v24, v142
	v_mov_b32_e32 v25, v143
	v_mul_f32_e32 v12, v38, v77
	v_mul_f32_e32 v30, v40, v77
	v_mul_f32_e32 v13, v39, v77
	v_mul_f32_e32 v31, v41, v77
	v_mul_f32_e32 v12, v12, v22
	v_mul_f32_e32 v22, v30, v24
	v_mul_f32_e32 v13, v13, v23
	v_mul_f32_e32 v23, v31, v25
	v_bfe_u32 v24, v12, 16, 1
	v_bfe_u32 v30, v22, 16, 1
	v_bfe_u32 v25, v13, 16, 1
	v_bfe_u32 v31, v23, 16, 1
	v_add3_u32 v12, v12, v24, s26
	v_add3_u32 v22, v22, v30, s26
	v_add3_u32 v13, v13, v25, s26
	v_add3_u32 v23, v23, v31, s26
	v_lshrrev_b32_e32 v12, 16, v12
	v_lshrrev_b32_e32 v22, 16, v22
	v_and_or_b32 v12, v13, s27, v12
	v_and_or_b32 v13, v23, s27, v22
	global_store_dwordx2 v[10:11], v[12:13], off offset:1024
	v_mov_b32_e32 v22, v144
	v_mov_b32_e32 v23, v145
	v_mov_b32_e32 v24, v146
	v_mov_b32_e32 v25, v147
	v_mul_f32_e32 v12, v26, v77
	v_mul_f32_e32 v26, v28, v77
	v_mul_f32_e32 v13, v27, v77
	v_mul_f32_e32 v27, v29, v77
	v_add_co_u32_e32 v30, vcc, s24, v54
	v_mul_f32_e32 v12, v12, v22
	v_mul_f32_e32 v22, v26, v24
	v_mul_f32_e32 v13, v13, v23
	v_mul_f32_e32 v23, v27, v25
	v_bfe_u32 v24, v12, 16, 1
	v_bfe_u32 v26, v22, 16, 1
	v_bfe_u32 v25, v13, 16, 1
	v_bfe_u32 v27, v23, 16, 1
	v_add3_u32 v12, v12, v24, s26
	v_add3_u32 v22, v22, v26, s26
	v_add3_u32 v13, v13, v25, s26
	v_add3_u32 v23, v23, v27, s26
	v_lshrrev_b32_e32 v12, 16, v12
	v_lshrrev_b32_e32 v22, 16, v22
	v_and_or_b32 v12, v13, s27, v12
	v_and_or_b32 v13, v23, s27, v22
	v_addc_co_u32_e32 v31, vcc, 0, v55, vcc
	global_store_dwordx2 v[10:11], v[12:13], off offset:1536
	v_mov_b32_e32 v22, v148
	v_mov_b32_e32 v23, v149
	v_mov_b32_e32 v24, v150
	v_mov_b32_e32 v25, v151
	v_mul_f32_e32 v12, v18, v77
	v_mul_f32_e32 v18, v20, v77
	v_mul_f32_e32 v13, v19, v77
	v_mul_f32_e32 v19, v21, v77
	v_mul_f32_e32 v12, v12, v22
	v_mul_f32_e32 v18, v18, v24
	v_mul_f32_e32 v13, v13, v23
	v_mul_f32_e32 v19, v19, v25
	v_bfe_u32 v20, v12, 16, 1
	v_bfe_u32 v22, v18, 16, 1
	v_bfe_u32 v21, v13, 16, 1
	v_bfe_u32 v23, v19, 16, 1
	v_add3_u32 v12, v12, v20, s26
	v_add3_u32 v18, v18, v22, s26
	v_add3_u32 v13, v13, v21, s26
	v_add3_u32 v19, v19, v23, s26
	v_lshrrev_b32_e32 v12, 16, v12
	v_lshrrev_b32_e32 v18, 16, v18
	v_and_or_b32 v12, v13, s27, v12
	v_and_or_b32 v13, v19, s27, v18
	global_store_dwordx2 v[10:11], v[12:13], off offset:2048
	v_mov_b32_e32 v18, v152
	v_mov_b32_e32 v19, v153
	v_mov_b32_e32 v20, v154
	v_mov_b32_e32 v21, v155
	v_mul_f32_e32 v12, v14, v77
	v_mul_f32_e32 v14, v16, v77
	v_mul_f32_e32 v13, v15, v77
	v_mul_f32_e32 v15, v17, v77
	v_mul_f32_e32 v12, v12, v18
	v_mul_f32_e32 v14, v14, v20
	v_mul_f32_e32 v13, v13, v19
	v_mul_f32_e32 v15, v15, v21
	v_bfe_u32 v16, v12, 16, 1
	v_bfe_u32 v18, v14, 16, 1
	v_bfe_u32 v17, v13, 16, 1
	v_bfe_u32 v19, v15, 16, 1
	v_add3_u32 v12, v12, v16, s26
	v_add3_u32 v14, v14, v18, s26
	v_add3_u32 v13, v13, v17, s26
	v_add3_u32 v15, v15, v19, s26
	v_lshrrev_b32_e32 v12, 16, v12
	v_lshrrev_b32_e32 v14, 16, v14
	v_and_or_b32 v12, v13, s27, v12
	v_and_or_b32 v13, v15, s27, v14
	global_store_dwordx2 v[10:11], v[12:13], off offset:2560
	v_mov_b32_e32 v12, v156
	v_mov_b32_e32 v13, v157
	v_mov_b32_e32 v14, v158
	v_mov_b32_e32 v15, v159
	v_mul_f32_e32 v6, v6, v12
	v_mul_f32_e32 v8, v8, v14
	v_mul_f32_e32 v7, v7, v13
	v_mul_f32_e32 v9, v9, v15
	v_bfe_u32 v12, v6, 16, 1
	v_bfe_u32 v14, v8, 16, 1
	v_bfe_u32 v13, v7, 16, 1
	v_bfe_u32 v15, v9, 16, 1
	v_add3_u32 v6, v6, v12, s26
	v_add3_u32 v8, v8, v14, s26
	v_add3_u32 v7, v7, v13, s26
	v_add3_u32 v9, v9, v15, s26
	v_lshrrev_b32_e32 v6, 16, v6
	v_lshrrev_b32_e32 v8, 16, v8
	v_and_or_b32 v6, v7, s27, v6
	v_and_or_b32 v7, v9, s27, v8
	global_store_dwordx2 v[10:11], v[6:7], off offset:3072
	v_mov_b32_e32 v6, v160
	v_mov_b32_e32 v7, v161
	v_mov_b32_e32 v8, v162
	v_mov_b32_e32 v9, v163
	v_mul_f32_e32 v2, v2, v6
	v_mul_f32_e32 v4, v4, v8
	v_mul_f32_e32 v3, v3, v7
	v_mul_f32_e32 v5, v5, v9
	v_bfe_u32 v6, v2, 16, 1
	v_bfe_u32 v8, v4, 16, 1
	v_bfe_u32 v7, v3, 16, 1
	v_bfe_u32 v9, v5, 16, 1
	v_add3_u32 v2, v2, v6, s26
	v_add3_u32 v4, v4, v8, s26
	v_add3_u32 v3, v3, v7, s26
	v_add3_u32 v5, v5, v9, s26
	v_lshrrev_b32_e32 v2, 16, v2
	v_lshrrev_b32_e32 v4, 16, v4
	v_and_or_b32 v2, v3, s27, v2
	v_and_or_b32 v3, v5, s27, v4
	global_store_dwordx2 v[10:11], v[2:3], off offset:3584
	s_cbranch_scc1 .LBB0_20
